# K-loops: removed mid-block s_setprio 0/1 pairs and the redundant lgkmcnt(0) at MFMA block heads
# baseline (speedup 1.0000x reference)
; #define PG8_STAGE(bufoff, gbase, voff) do { _Pragma("unroll") for (int _i = 0; _i < 2; ++_i) \
;         __builtin_amdgcn_global_load_lds((const unsigned*)((const char*)(gbase) + (voff)[_i]), (PG8_LAS unsigned*)(lds + (bufoff) + ldsw + _i * 8192), 16, 0, 0); } while (0)
; #define PG8_LDA(dst, b, h) do { _Pragma("unroll") for (int m = 0; m < 4; ++m) _Pragma("unroll") for (int k = 0; k < 2; ++k) dst[m][k] = *(const PG8_LAS bf16x8*)(lds + PG8_SA(b, h) + aoff + m * 2048 + k * 1024); } while (0)
; #define PG8_LDB(dst, b, h) do { _Pragma("unroll") for (int n = 0; n < 2; ++n) _Pragma("unroll") for (int k = 0; k < 2; ++k) dst[n][k] = *(const PG8_LAS bf16x8*)(lds + PG8_SB(b, h) + boff + n * 2048 + k * 1024); } while (0)
; #define PG8_MMA(ai, bj, At, Bt) do { __builtin_amdgcn_s_setprio(1); _Pragma("unroll") for (int m = 0; m < 4; ++m) _Pragma("unroll") for (int n = 0; n < 2; ++n) _Pragma("unroll") for (int k = 0; k < 2; ++k) \
;         acc[ai][bj][m][n] = __builtin_amdgcn_mfma_f32_16x16x32_bf16(Bt[n][k], At[m][k], acc[ai][bj][m][n], 0, 0, 0); __builtin_amdgcn_s_setprio(0); } while (0)
; #define PG8_WAIT_V(n) asm volatile("s_waitcnt vmcnt(" #n ")" ::: "memory")
; #define PG8_WAIT_L(n) asm volatile("s_waitcnt lgkmcnt(" #n ")" ::: "memory")
; #define PG8_BAR __builtin_amdgcn_s_barrier()
; template <class Epi, class Sched, bool ALIGN_EPI = false, bool SP2 = false>
; __device__ __forceinline__ void gemm_phase(PG8_LAS unsigned char* lds, const Gemm g, const Sched& S, const Epi& E, const int wave_s) {
;     ...
;             const char* a1 = cA + (size_t)(t + 1) * kstep;
;             const char* a2 = last ? nA : cA + (size_t)(t + 2) * kstep; const char* b2 = last ? nB : cB + (size_t)(t + 2) * kstep;
;             const char* a3 = a2 + kstep; const char* b3 = b2 + kstep;
;             if (last && has_next) S.a_ready(nxt);
;             if constexpr (SP2) {
;             PG8_LDB(B0, 0, 0); PG8_LDB(B1, 0, 1); PG8_SCHED; PG8_LDA(At, 0, 0); PG8_STAGE(PG8_SA(1, 1), a1 + hstep, voffA);
;             PG8_WAIT_V(8); PG8_WAIT_L(0); PG8_BAR; PG8_MMA(0, 0, At, B0); PG8_MMA(0, 1, At, B1); PG8_BAR; PG8_SCHED;
;             PG8_LDA(At, 0, 1); PG8_STAGE(PG8_SB(0, 0), b2, voffB); PG8_STAGE(PG8_SB(0, 1), b2 + hstep, voffB); PG8_STAGE(PG8_SA(0, 0), a2, voffA);
;             PG8_WAIT_V(8); PG8_WAIT_L(0); PG8_BAR; PG8_MMA(1, 0, At, B0); PG8_MMA(1, 1, At, B1); PG8_BAR; PG8_SCHED;
.LBB0_301:
	s_add_u32 s2, s34, 0xfffc0080
	s_addc_u32 s3, s35, -1
	s_add_i32 s55, 0, 0x10000
	s_cmp_eq_u32 s54, 12
	s_cselect_b32 s37, s9, s3
	s_cselect_b32 s36, s25, s2
	s_cselect_b32 s3, s23, s53
	s_cselect_b32 s2, s31, s52
	s_add_i32 s58, 0, 0x14000
	v_add_u32_e32 v156, s55, v146
	v_add_u32_e32 v160, s58, v146
	ds_read_b128 v[140:143], v156
	ds_read_b128 v[148:151], v156 offset:1024
	ds_read_b128 v[152:155], v156 offset:2048
	ds_read_b128 v[156:159], v156 offset:3072
	ds_read_b128 v[174:177], v160
	ds_read_b128 v[178:181], v160 offset:1024
	ds_read_b128 v[182:185], v160 offset:2048
	ds_read_b128 v[186:189], v160 offset:3072
	v_lshl_add_u64 v[160:161], s[34:35], 0, v[136:137]
	s_add_i32 m0, s43, 0xc000
	ds_read_b128 v[190:193], v147
	ds_read_b128 v[210:213], v147 offset:1024
	ds_read_b128 v[214:217], v147 offset:2048
	ds_read_b128 v[218:221], v147 offset:3072
	ds_read_b128 v[222:225], v147 offset:4096
	ds_read_b128 v[226:229], v147 offset:5120
	ds_read_b128 v[230:233], v147 offset:6144
	ds_read_b128 v[234:237], v147 offset:7168
	global_load_lds_dwordx4 v[160:161], off
	v_lshl_add_u64 v[160:161], s[34:35], 0, v[138:139]
	s_add_i32 m0, s43, 0xe000
	s_nop 0
	global_load_lds_dwordx4 v[160:161], off
	s_waitcnt vmcnt(8)
	s_waitcnt lgkmcnt(0)
	s_barrier
	s_setprio 1
	v_mfma_f32_16x16x32_bf16 v[124:127], v[140:143], v[190:193], v[124:127]
	v_mfma_f32_16x16x32_bf16 v[120:123], v[152:155], v[190:193], v[120:123]
	v_mfma_f32_16x16x32_bf16 v[108:111], v[140:143], v[214:217], v[108:111]
	v_mfma_f32_16x16x32_bf16 v[104:107], v[152:155], v[214:217], v[104:107]
	v_mfma_f32_16x16x32_bf16 v[92:95], v[140:143], v[222:225], v[92:95]
	v_mfma_f32_16x16x32_bf16 v[88:91], v[152:155], v[222:225], v[88:91]
	v_mfma_f32_16x16x32_bf16 v[76:79], v[140:143], v[230:233], v[76:79]
	v_mfma_f32_16x16x32_bf16 v[72:75], v[152:155], v[230:233], v[72:75]
	v_mfma_f32_16x16x32_bf16 v[124:127], v[148:151], v[210:213], v[124:127]
	v_mfma_f32_16x16x32_bf16 v[120:123], v[156:159], v[210:213], v[120:123]
	v_mfma_f32_16x16x32_bf16 v[108:111], v[148:151], v[218:221], v[108:111]
	v_mfma_f32_16x16x32_bf16 v[104:107], v[156:159], v[218:221], v[104:107]
	v_mfma_f32_16x16x32_bf16 v[92:95], v[148:151], v[226:229], v[92:95]
	v_mfma_f32_16x16x32_bf16 v[88:91], v[156:159], v[226:229], v[88:91]
	v_mfma_f32_16x16x32_bf16 v[76:79], v[148:151], v[234:237], v[76:79]
	v_mfma_f32_16x16x32_bf16 v[72:75], v[156:159], v[234:237], v[72:75]
	v_mfma_f32_16x16x32_bf16 v[116:119], v[174:177], v[190:193], v[116:119]
	v_mfma_f32_16x16x32_bf16 v[112:115], v[182:185], v[190:193], v[112:115]
	v_mfma_f32_16x16x32_bf16 v[100:103], v[174:177], v[214:217], v[100:103]
	v_mfma_f32_16x16x32_bf16 v[96:99], v[182:185], v[214:217], v[96:99]
	v_mfma_f32_16x16x32_bf16 v[84:87], v[174:177], v[222:225], v[84:87]
	v_mfma_f32_16x16x32_bf16 v[80:83], v[182:185], v[222:225], v[80:83]
	v_mfma_f32_16x16x32_bf16 v[68:71], v[174:177], v[230:233], v[68:71]
	v_mfma_f32_16x16x32_bf16 v[64:67], v[182:185], v[230:233], v[64:67]
	v_mfma_f32_16x16x32_bf16 v[116:119], v[178:181], v[210:213], v[116:119]
	v_mfma_f32_16x16x32_bf16 v[112:115], v[186:189], v[210:213], v[112:115]
	v_mfma_f32_16x16x32_bf16 v[100:103], v[178:181], v[218:221], v[100:103]
	v_mfma_f32_16x16x32_bf16 v[96:99], v[186:189], v[218:221], v[96:99]
	v_mfma_f32_16x16x32_bf16 v[84:87], v[178:181], v[226:229], v[84:87]
	v_mfma_f32_16x16x32_bf16 v[80:83], v[186:189], v[226:229], v[80:83]
	v_mfma_f32_16x16x32_bf16 v[68:71], v[178:181], v[234:237], v[68:71]
	v_mfma_f32_16x16x32_bf16 v[64:67], v[186:189], v[234:237], v[64:67]
	s_setprio 0
	s_barrier
	s_add_i32 s55, s55, s42
	v_lshl_add_u64 v[160:161], s[2:3], 0, v[128:129]
	s_mov_b32 m0, s55
	ds_read_b128 v[190:193], v147 offset:16384
	ds_read_b128 v[210:213], v147 offset:17408
	ds_read_b128 v[214:217], v147 offset:18432
	ds_read_b128 v[218:221], v147 offset:19456
	ds_read_b128 v[222:225], v147 offset:20480
	ds_read_b128 v[226:229], v147 offset:21504
	ds_read_b128 v[230:233], v147 offset:22528
	ds_read_b128 v[234:237], v147 offset:23552
	global_load_lds_dwordx4 v[160:161], off
	s_add_i32 m0, s55, 0x2000
	s_add_u32 s56, s2, 0x40000
	v_lshl_add_u64 v[194:195], s[2:3], 0, v[134:135]
	s_addc_u32 s57, s3, 0
	s_add_i32 s55, s58, s42
	global_load_lds_dwordx4 v[194:195], off
	v_lshl_add_u64 v[206:207], s[56:57], 0, v[128:129]
	s_mov_b32 m0, s55
	v_lshl_add_u64 v[238:239], s[36:37], 0, v[132:133]
	global_load_lds_dwordx4 v[206:207], off
	v_lshl_add_u64 v[206:207], s[56:57], 0, v[134:135]
	s_add_i32 m0, s55, 0x2000
	s_nop 0
	global_load_lds_dwordx4 v[206:207], off
	v_lshl_add_u64 v[206:207], s[36:37], 0, v[130:131]
	s_mov_b32 m0, s43
	s_nop 0
	global_load_lds_dwordx4 v[206:207], off
	s_mov_b32 m0, s44
	s_nop 0
	global_load_lds_dwordx4 v[238:239], off
	s_waitcnt vmcnt(8)
	s_waitcnt lgkmcnt(0)
	s_barrier
; #define PG8_STAGE(bufoff, gbase, voff) do { _Pragma("unroll") for (int _i = 0; _i < 2; ++_i) \
;         __builtin_amdgcn_global_load_lds((const unsigned*)((const char*)(gbase) + (voff)[_i]), (PG8_LAS unsigned*)(lds + (bufoff) + ldsw + _i * 8192), 16, 0, 0); } while (0)
; #define PG8_LDA(dst, b, h) do { _Pragma("unroll") for (int m = 0; m < 4; ++m) _Pragma("unroll") for (int k = 0; k < 2; ++k) dst[m][k] = *(const PG8_LAS bf16x8*)(lds + PG8_SA(b, h) + aoff + m * 2048 + k * 1024); } while (0)
; #define PG8_LDB(dst, b, h) do { _Pragma("unroll") for (int n = 0; n < 2; ++n) _Pragma("unroll") for (int k = 0; k < 2; ++k) dst[n][k] = *(const PG8_LAS bf16x8*)(lds + PG8_SB(b, h) + boff + n * 2048 + k * 1024); } while (0)
; #define PG8_MMA(ai, bj, At, Bt) do { __builtin_amdgcn_s_setprio(1); _Pragma("unroll") for (int m = 0; m < 4; ++m) _Pragma("unroll") for (int n = 0; n < 2; ++n) _Pragma("unroll") for (int k = 0; k < 2; ++k) \
;         acc[ai][bj][m][n] = __builtin_amdgcn_mfma_f32_16x16x32_bf16(Bt[n][k], At[m][k], acc[ai][bj][m][n], 0, 0, 0); __builtin_amdgcn_s_setprio(0); } while (0)
; #define PG8_WAIT_V(n) asm volatile("s_waitcnt vmcnt(" #n ")" ::: "memory")
; #define PG8_WAIT_L(n) asm volatile("s_waitcnt lgkmcnt(" #n ")" ::: "memory")
; #define PG8_BAR __builtin_amdgcn_s_barrier()
; #define PG8_SCHED __builtin_amdgcn_sched_barrier(0)
; template <class Epi, class Sched, bool ALIGN_EPI = false, bool SP2 = false>
; __device__ __forceinline__ void gemm_phase(PG8_LAS unsigned char* lds, const Gemm g, const Sched& S, const Epi& E, const int wave_s) {
;     ...
;             PG8_WAIT_V(8); PG8_WAIT_L(0); PG8_BAR; PG8_MMA(1, 0, At, B0); PG8_MMA(1, 1, At, B1); PG8_BAR; PG8_SCHED;
;             PG8_LDB(B0, 1, 0); PG8_LDB(B1, 1, 1); PG8_SCHED; PG8_LDA(At, 1, 0); PG8_STAGE(PG8_SA(0, 1), a2 + hstep, voffA);
;             PG8_WAIT_V(8); PG8_WAIT_L(0); PG8_BAR; PG8_MMA(0, 0, At, B0); PG8_MMA(0, 1, At, B1); PG8_BAR; PG8_SCHED;
	s_setprio 1
	v_mfma_f32_16x16x32_bf16 v[60:63], v[140:143], v[190:193], v[60:63]
	v_mfma_f32_16x16x32_bf16 v[56:59], v[152:155], v[190:193], v[56:59]
	v_mfma_f32_16x16x32_bf16 v[44:47], v[140:143], v[214:217], v[44:47]
	v_mfma_f32_16x16x32_bf16 v[40:43], v[152:155], v[214:217], v[40:43]
	v_mfma_f32_16x16x32_bf16 v[28:31], v[140:143], v[222:225], v[28:31]
	v_mfma_f32_16x16x32_bf16 v[24:27], v[152:155], v[222:225], v[24:27]
	v_mfma_f32_16x16x32_bf16 v[12:15], v[140:143], v[230:233], v[12:15]
	v_mfma_f32_16x16x32_bf16 v[8:11], v[152:155], v[230:233], v[8:11]
	v_mfma_f32_16x16x32_bf16 v[60:63], v[148:151], v[210:213], v[60:63]
	v_mfma_f32_16x16x32_bf16 v[56:59], v[156:159], v[210:213], v[56:59]
	v_mfma_f32_16x16x32_bf16 v[44:47], v[148:151], v[218:221], v[44:47]
	v_mfma_f32_16x16x32_bf16 v[40:43], v[156:159], v[218:221], v[40:43]
	v_mfma_f32_16x16x32_bf16 v[28:31], v[148:151], v[226:229], v[28:31]
	v_mfma_f32_16x16x32_bf16 v[24:27], v[156:159], v[226:229], v[24:27]
	v_mfma_f32_16x16x32_bf16 v[12:15], v[148:151], v[234:237], v[12:15]
	v_mfma_f32_16x16x32_bf16 v[8:11], v[156:159], v[234:237], v[8:11]
	v_mfma_f32_16x16x32_bf16 v[52:55], v[174:177], v[190:193], v[52:55]
	v_mfma_f32_16x16x32_bf16 v[48:51], v[182:185], v[190:193], v[48:51]
	v_mfma_f32_16x16x32_bf16 v[36:39], v[174:177], v[214:217], v[36:39]
	v_mfma_f32_16x16x32_bf16 v[32:35], v[182:185], v[214:217], v[32:35]
	v_mfma_f32_16x16x32_bf16 v[20:23], v[174:177], v[222:225], v[20:23]
	v_mfma_f32_16x16x32_bf16 v[16:19], v[182:185], v[222:225], v[16:19]
	v_mfma_f32_16x16x32_bf16 v[4:7], v[174:177], v[230:233], v[4:7]
	v_mfma_f32_16x16x32_bf16 v[0:3], v[182:185], v[230:233], v[0:3]
	v_mfma_f32_16x16x32_bf16 v[52:55], v[178:181], v[210:213], v[52:55]
	v_mfma_f32_16x16x32_bf16 v[48:51], v[186:189], v[210:213], v[48:51]
	v_mfma_f32_16x16x32_bf16 v[36:39], v[178:181], v[218:221], v[36:39]
	v_mfma_f32_16x16x32_bf16 v[32:35], v[186:189], v[218:221], v[32:35]
	v_mfma_f32_16x16x32_bf16 v[20:23], v[178:181], v[226:229], v[20:23]
	v_mfma_f32_16x16x32_bf16 v[16:19], v[186:189], v[226:229], v[16:19]
	v_mfma_f32_16x16x32_bf16 v[4:7], v[178:181], v[234:237], v[4:7]
	v_mfma_f32_16x16x32_bf16 v[0:3], v[186:189], v[234:237], v[0:3]
	s_setprio 0
	s_barrier
	s_add_i32 s55, 0, 0x18000
	s_add_i32 s56, 0, 0x1c000
	v_add_u32_e32 v156, s55, v146
	v_add_u32_e32 v171, s56, v146
	ds_read_b128 v[140:143], v156
	ds_read_b128 v[148:151], v156 offset:1024
	ds_read_b128 v[152:155], v156 offset:2048
	ds_read_b128 v[156:159], v156 offset:3072
	ds_read_b128 v[174:177], v171
	ds_read_b128 v[178:181], v171 offset:1024
	ds_read_b128 v[182:185], v171 offset:2048
	ds_read_b128 v[186:189], v171 offset:3072
	s_add_u32 s36, s36, 0x40000
	s_addc_u32 s37, s37, 0
	s_mov_b32 m0, s45
	v_lshl_add_u64 v[240:241], s[36:37], 0, v[130:131]
	ds_read_b128 v[190:193], v147 offset:32768
	ds_read_b128 v[210:213], v147 offset:33792
	ds_read_b128 v[214:217], v147 offset:34816
	ds_read_b128 v[218:221], v147 offset:35840
	ds_read_b128 v[222:225], v147 offset:36864
	ds_read_b128 v[226:229], v147 offset:37888
	ds_read_b128 v[230:233], v147 offset:38912
	ds_read_b128 v[234:237], v147 offset:39936
	global_load_lds_dwordx4 v[240:241], off
	v_lshl_add_u64 v[240:241], s[36:37], 0, v[132:133]
	s_mov_b32 m0, s46
	s_nop 0
	global_load_lds_dwordx4 v[240:241], off
	s_waitcnt vmcnt(8)
	s_waitcnt lgkmcnt(0)
	s_barrier
	s_setprio 1
	v_mfma_f32_16x16x32_bf16 v[124:127], v[140:143], v[190:193], v[124:127]
	v_mfma_f32_16x16x32_bf16 v[120:123], v[152:155], v[190:193], v[120:123]
	v_mfma_f32_16x16x32_bf16 v[108:111], v[140:143], v[214:217], v[108:111]
	v_mfma_f32_16x16x32_bf16 v[104:107], v[152:155], v[214:217], v[104:107]
	v_mfma_f32_16x16x32_bf16 v[92:95], v[140:143], v[222:225], v[92:95]
	v_mfma_f32_16x16x32_bf16 v[88:91], v[152:155], v[222:225], v[88:91]
	v_mfma_f32_16x16x32_bf16 v[76:79], v[140:143], v[230:233], v[76:79]
	v_mfma_f32_16x16x32_bf16 v[72:75], v[152:155], v[230:233], v[72:75]
	v_mfma_f32_16x16x32_bf16 v[124:127], v[148:151], v[210:213], v[124:127]
	v_mfma_f32_16x16x32_bf16 v[120:123], v[156:159], v[210:213], v[120:123]
	v_mfma_f32_16x16x32_bf16 v[108:111], v[148:151], v[218:221], v[108:111]
	v_mfma_f32_16x16x32_bf16 v[104:107], v[156:159], v[218:221], v[104:107]
	v_mfma_f32_16x16x32_bf16 v[92:95], v[148:151], v[226:229], v[92:95]
	v_mfma_f32_16x16x32_bf16 v[88:91], v[156:159], v[226:229], v[88:91]
	v_mfma_f32_16x16x32_bf16 v[76:79], v[148:151], v[234:237], v[76:79]
	v_mfma_f32_16x16x32_bf16 v[72:75], v[156:159], v[234:237], v[72:75]
	v_mfma_f32_16x16x32_bf16 v[116:119], v[174:177], v[190:193], v[116:119]
	v_mfma_f32_16x16x32_bf16 v[112:115], v[182:185], v[190:193], v[112:115]
	v_mfma_f32_16x16x32_bf16 v[100:103], v[174:177], v[214:217], v[100:103]
	v_mfma_f32_16x16x32_bf16 v[96:99], v[182:185], v[214:217], v[96:99]
	v_mfma_f32_16x16x32_bf16 v[84:87], v[174:177], v[222:225], v[84:87]
	v_mfma_f32_16x16x32_bf16 v[80:83], v[182:185], v[222:225], v[80:83]
	v_mfma_f32_16x16x32_bf16 v[68:71], v[174:177], v[230:233], v[68:71]
	v_mfma_f32_16x16x32_bf16 v[64:67], v[182:185], v[230:233], v[64:67]
	v_mfma_f32_16x16x32_bf16 v[116:119], v[178:181], v[210:213], v[116:119]
	v_mfma_f32_16x16x32_bf16 v[112:115], v[186:189], v[210:213], v[112:115]
	v_mfma_f32_16x16x32_bf16 v[100:103], v[178:181], v[218:221], v[100:103]
	v_mfma_f32_16x16x32_bf16 v[96:99], v[186:189], v[218:221], v[96:99]
	v_mfma_f32_16x16x32_bf16 v[84:87], v[178:181], v[226:229], v[84:87]
	v_mfma_f32_16x16x32_bf16 v[80:83], v[186:189], v[226:229], v[80:83]
	v_mfma_f32_16x16x32_bf16 v[68:71], v[178:181], v[234:237], v[68:71]
	v_mfma_f32_16x16x32_bf16 v[64:67], v[186:189], v[234:237], v[64:67]
	s_setprio 0
	s_barrier
; #define PG8_STAGE(bufoff, gbase, voff) do { _Pragma("unroll") for (int _i = 0; _i < 2; ++_i) \
;         __builtin_amdgcn_global_load_lds((const unsigned*)((const char*)(gbase) + (voff)[_i]), (PG8_LAS unsigned*)(lds + (bufoff) + ldsw + _i * 8192), 16, 0, 0); } while (0)
; #define PG8_LDA(dst, b, h) do { _Pragma("unroll") for (int m = 0; m < 4; ++m) _Pragma("unroll") for (int k = 0; k < 2; ++k) dst[m][k] = *(const PG8_LAS bf16x8*)(lds + PG8_SA(b, h) + aoff + m * 2048 + k * 1024); } while (0)
; #define PG8_MMA(ai, bj, At, Bt) do { __builtin_amdgcn_s_setprio(1); _Pragma("unroll") for (int m = 0; m < 4; ++m) _Pragma("unroll") for (int n = 0; n < 2; ++n) _Pragma("unroll") for (int k = 0; k < 2; ++k) \
;         acc[ai][bj][m][n] = __builtin_amdgcn_mfma_f32_16x16x32_bf16(Bt[n][k], At[m][k], acc[ai][bj][m][n], 0, 0, 0); __builtin_amdgcn_s_setprio(0); } while (0)
; #define PG8_WAIT_V(n) asm volatile("s_waitcnt vmcnt(" #n ")" ::: "memory")
; #define PG8_WAIT_L(n) asm volatile("s_waitcnt lgkmcnt(" #n ")" ::: "memory")
; #define PG8_BAR __builtin_amdgcn_s_barrier()
; #define PG8_SCHED __builtin_amdgcn_sched_barrier(0)
; template <class Epi, class Sched, bool ALIGN_EPI = false, bool SP2 = false>
; __device__ __forceinline__ void gemm_phase(PG8_LAS unsigned char* lds, const Gemm g, const Sched& S, const Epi& E, const int wave_s) {
;     ...
;             PG8_LDA(At, 1, 1); PG8_STAGE(PG8_SB(1, 0), b3, voffB); PG8_STAGE(PG8_SB(1, 1), b3 + hstep, voffB); PG8_STAGE(PG8_SA(1, 0), a3, voffA);
;             PG8_WAIT_V(8); PG8_WAIT_L(0); PG8_BAR; PG8_MMA(1, 0, At, B0); PG8_MMA(1, 1, At, B1); PG8_BAR; PG8_SCHED;
	s_add_i32 s36, s55, s42
	v_lshl_add_u64 v[160:161], v[160:161], 0, s[4:5]
	s_mov_b32 m0, s36
	ds_read_b128 v[190:193], v147 offset:49152
	ds_read_b128 v[210:213], v147 offset:50176
	ds_read_b128 v[214:217], v147 offset:51200
	ds_read_b128 v[218:221], v147 offset:52224
	ds_read_b128 v[222:225], v147 offset:53248
	ds_read_b128 v[226:229], v147 offset:54272
	ds_read_b128 v[230:233], v147 offset:55296
	ds_read_b128 v[234:237], v147 offset:56320
	global_load_lds_dwordx4 v[160:161], off
	s_add_i32 m0, s36, 0x2000
	s_add_u32 s2, s2, 0x40080
	v_lshl_add_u64 v[160:161], v[194:195], 0, s[4:5]
	s_addc_u32 s3, s3, 0
	s_add_i32 s36, s56, s42
	global_load_lds_dwordx4 v[160:161], off
	v_lshl_add_u64 v[160:161], s[2:3], 0, v[128:129]
	s_mov_b32 m0, s36
	s_nop 0
	global_load_lds_dwordx4 v[160:161], off
	v_lshl_add_u64 v[160:161], s[2:3], 0, v[134:135]
	s_add_i32 m0, s36, 0x2000
	s_nop 0
	global_load_lds_dwordx4 v[160:161], off
	v_lshl_add_u64 v[160:161], v[206:207], 0, s[4:5]
	s_mov_b32 m0, s49
	s_nop 0
	global_load_lds_dwordx4 v[160:161], off
	v_lshl_add_u64 v[160:161], v[238:239], 0, s[4:5]
	s_mov_b32 m0, s50
	s_nop 0
	global_load_lds_dwordx4 v[160:161], off
	s_waitcnt vmcnt(8)
	s_waitcnt lgkmcnt(0)
	s_barrier
	s_setprio 1
	v_mfma_f32_16x16x32_bf16 v[60:63], v[140:143], v[190:193], v[60:63]
	v_mfma_f32_16x16x32_bf16 v[56:59], v[152:155], v[190:193], v[56:59]
	v_mfma_f32_16x16x32_bf16 v[44:47], v[140:143], v[214:217], v[44:47]
	v_mfma_f32_16x16x32_bf16 v[40:43], v[152:155], v[214:217], v[40:43]
	v_mfma_f32_16x16x32_bf16 v[28:31], v[140:143], v[222:225], v[28:31]
	v_mfma_f32_16x16x32_bf16 v[24:27], v[152:155], v[222:225], v[24:27]
	v_mfma_f32_16x16x32_bf16 v[12:15], v[140:143], v[230:233], v[12:15]
	v_mfma_f32_16x16x32_bf16 v[8:11], v[152:155], v[230:233], v[8:11]
	v_mfma_f32_16x16x32_bf16 v[60:63], v[148:151], v[210:213], v[60:63]
	v_mfma_f32_16x16x32_bf16 v[56:59], v[156:159], v[210:213], v[56:59]
	v_mfma_f32_16x16x32_bf16 v[44:47], v[148:151], v[218:221], v[44:47]
	v_mfma_f32_16x16x32_bf16 v[40:43], v[156:159], v[218:221], v[40:43]
	v_mfma_f32_16x16x32_bf16 v[28:31], v[148:151], v[226:229], v[28:31]
	v_mfma_f32_16x16x32_bf16 v[24:27], v[156:159], v[226:229], v[24:27]
	v_mfma_f32_16x16x32_bf16 v[12:15], v[148:151], v[234:237], v[12:15]
	v_mfma_f32_16x16x32_bf16 v[8:11], v[156:159], v[234:237], v[8:11]
	v_mfma_f32_16x16x32_bf16 v[52:55], v[174:177], v[190:193], v[52:55]
	v_mfma_f32_16x16x32_bf16 v[48:51], v[182:185], v[190:193], v[48:51]
	v_mfma_f32_16x16x32_bf16 v[36:39], v[174:177], v[214:217], v[36:39]
	v_mfma_f32_16x16x32_bf16 v[32:35], v[182:185], v[214:217], v[32:35]
	v_mfma_f32_16x16x32_bf16 v[20:23], v[174:177], v[222:225], v[20:23]
	v_mfma_f32_16x16x32_bf16 v[16:19], v[182:185], v[222:225], v[16:19]
	v_mfma_f32_16x16x32_bf16 v[4:7], v[174:177], v[230:233], v[4:7]
	v_mfma_f32_16x16x32_bf16 v[0:3], v[182:185], v[230:233], v[0:3]
	v_mfma_f32_16x16x32_bf16 v[52:55], v[178:181], v[210:213], v[52:55]
	v_mfma_f32_16x16x32_bf16 v[48:51], v[186:189], v[210:213], v[48:51]
	v_mfma_f32_16x16x32_bf16 v[36:39], v[178:181], v[218:221], v[36:39]
	v_mfma_f32_16x16x32_bf16 v[32:35], v[186:189], v[218:221], v[32:35]
	v_mfma_f32_16x16x32_bf16 v[20:23], v[178:181], v[226:229], v[20:23]
	v_mfma_f32_16x16x32_bf16 v[16:19], v[186:189], v[226:229], v[16:19]
	v_mfma_f32_16x16x32_bf16 v[4:7], v[178:181], v[234:237], v[4:7]
	v_mfma_f32_16x16x32_bf16 v[0:3], v[186:189], v[234:237], v[0:3]
	s_setprio 0
	s_barrier
	s_add_i32 s54, s54, 2
	s_add_u32 s34, s34, 0x100
	s_addc_u32 s35, s35, 0
	s_add_u32 s52, s52, 0x100
	s_addc_u32 s53, s53, 0
	s_cmp_gt_u32 s54, 13
	s_cbranch_scc0 .LBB0_301
	s_and_b64 vcc, exec, s[20:21]
	s_cbranch_vccz .LBB0_304
	s_barrier

; #define PG8_STAGE(bufoff, gbase, voff) do { _Pragma("unroll") for (int _i = 0; _i < 2; ++_i) \
;         __builtin_amdgcn_global_load_lds((const unsigned*)((const char*)(gbase) + (voff)[_i]), (PG8_LAS unsigned*)(lds + (bufoff) + ldsw + _i * 8192), 16, 0, 0); } while (0)
; #define PG8_LDA(dst, b, h) do { _Pragma("unroll") for (int m = 0; m < 4; ++m) _Pragma("unroll") for (int k = 0; k < 2; ++k) dst[m][k] = *(const PG8_LAS bf16x8*)(lds + PG8_SA(b, h) + aoff + m * 2048 + k * 1024); } while (0)
; #define PG8_LDB(dst, b, h) do { _Pragma("unroll") for (int n = 0; n < 2; ++n) _Pragma("unroll") for (int k = 0; k < 2; ++k) dst[n][k] = *(const PG8_LAS bf16x8*)(lds + PG8_SB(b, h) + boff + n * 2048 + k * 1024); } while (0)
; #define PG8_MMA(ai, bj, At, Bt) do { __builtin_amdgcn_s_setprio(1); _Pragma("unroll") for (int m = 0; m < 4; ++m) _Pragma("unroll") for (int n = 0; n < 2; ++n) _Pragma("unroll") for (int k = 0; k < 2; ++k) \
;         acc[ai][bj][m][n] = __builtin_amdgcn_mfma_f32_16x16x32_bf16(Bt[n][k], At[m][k], acc[ai][bj][m][n], 0, 0, 0); __builtin_amdgcn_s_setprio(0); } while (0)
; #define PG8_WAIT_V(n) asm volatile("s_waitcnt vmcnt(" #n ")" ::: "memory")
; #define PG8_WAIT_L(n) asm volatile("s_waitcnt lgkmcnt(" #n ")" ::: "memory")
; template <class Epi, class Sched, bool ALIGN_EPI = false, bool SP2 = false>
; __device__ __forceinline__ void gemm_phase(PG8_LAS unsigned char* lds, const Gemm g, const Sched& S, const Epi& E, const int wave_s) {
;     ...
;             const bool last = (t == clen - 2);
;             const char* a1 = cA + (size_t)(t + 1) * kstep;
;             const char* a2 = last ? nA : cA + (size_t)(t + 2) * kstep; const char* b2 = last ? nB : cB + (size_t)(t + 2) * kstep;
;             const char* a3 = a2 + kstep; const char* b3 = b2 + kstep;
;             if (last && has_next) S.a_ready(nxt);
;             if constexpr (SP2) {
;             PG8_LDB(B0, 0, 0); PG8_LDB(B1, 0, 1); PG8_SCHED; PG8_LDA(At, 0, 0); PG8_STAGE(PG8_SA(1, 1), a1 + hstep, voffA);
;             PG8_WAIT_V(8); PG8_WAIT_L(0); PG8_BAR; PG8_MMA(0, 0, At, B0); PG8_MMA(0, 1, At, B1); PG8_BAR; PG8_SCHED;
;             PG8_LDA(At, 0, 1); PG8_STAGE(PG8_SB(0, 0), b2, voffB); PG8_STAGE(PG8_SB(0, 1), b2 + hstep, voffB); PG8_STAGE(PG8_SA(0, 0), a2, voffA);
;             PG8_WAIT_V(8); PG8_WAIT_L(0); PG8_BAR; PG8_MMA(1, 0, At, B0); PG8_MMA(1, 1, At, B1); PG8_BAR; PG8_SCHED;
.LBB0_369:
	s_add_i32 s59, s8, 2
	s_add_u32 s60, s34, 0x80
	s_addc_u32 s9, s35, 0
	s_add_i32 s62, 0, 0x10000
	s_cmp_eq_u32 s17, s8
	s_cselect_b32 s9, s29, s9
	s_cselect_b32 s8, s28, s60
	v_add_u32_e32 v128, s62, v142
	s_cselect_b32 s61, s31, s58
	s_cselect_b32 s60, s30, s57
	s_add_i32 s63, 0, 0x14000
	ds_read_b128 v[138:141], v128
	ds_read_b128 v[144:147], v128 offset:1024
	ds_read_b128 v[148:151], v128 offset:2048
	ds_read_b128 v[152:155], v128 offset:3072
	v_add_u32_e32 v128, s63, v142
	ds_read_b128 v[156:159], v128
	ds_read_b128 v[184:187], v128 offset:1024
	ds_read_b128 v[188:191], v128 offset:2048
	ds_read_b128 v[192:195], v128 offset:3072
	v_lshl_add_u64 v[130:131], s[34:35], 0, v[134:135]
	s_add_i32 m0, s44, 0xc000
	ds_read_b128 v[212:215], v143
	ds_read_b128 v[216:219], v143 offset:1024
	ds_read_b128 v[220:223], v143 offset:2048
	ds_read_b128 v[224:227], v143 offset:3072
	ds_read_b128 v[228:231], v143 offset:4096
	ds_read_b128 v[232:235], v143 offset:5120
	ds_read_b128 v[236:239], v143 offset:6144
	ds_read_b128 v[240:243], v143 offset:7168
	global_load_lds_dwordx4 v[130:131], off
	v_lshl_add_u64 v[130:131], s[34:35], 0, v[136:137]
	s_add_i32 m0, s44, 0xe000
	s_nop 0
	global_load_lds_dwordx4 v[130:131], off
	s_waitcnt vmcnt(8)
	s_waitcnt lgkmcnt(0)
	s_barrier
	s_setprio 1
	v_mfma_f32_16x16x32_bf16 v[96:99], v[138:141], v[212:215], v[96:99]
	v_mfma_f32_16x16x32_bf16 v[100:103], v[148:151], v[212:215], v[100:103]
	v_mfma_f32_16x16x32_bf16 v[104:107], v[138:141], v[220:223], v[104:107]
	v_mfma_f32_16x16x32_bf16 v[108:111], v[148:151], v[220:223], v[108:111]
	v_mfma_f32_16x16x32_bf16 v[112:115], v[138:141], v[228:231], v[112:115]
	v_mfma_f32_16x16x32_bf16 v[116:119], v[148:151], v[228:231], v[116:119]
	v_mfma_f32_16x16x32_bf16 v[120:123], v[138:141], v[236:239], v[120:123]
	v_mfma_f32_16x16x32_bf16 v[124:127], v[148:151], v[236:239], v[124:127]
	v_mfma_f32_16x16x32_bf16 v[96:99], v[144:147], v[216:219], v[96:99]
	v_mfma_f32_16x16x32_bf16 v[100:103], v[152:155], v[216:219], v[100:103]
	v_mfma_f32_16x16x32_bf16 v[104:107], v[144:147], v[224:227], v[104:107]
	v_mfma_f32_16x16x32_bf16 v[108:111], v[152:155], v[224:227], v[108:111]
	v_mfma_f32_16x16x32_bf16 v[112:115], v[144:147], v[232:235], v[112:115]
	v_mfma_f32_16x16x32_bf16 v[116:119], v[152:155], v[232:235], v[116:119]
	v_mfma_f32_16x16x32_bf16 v[120:123], v[144:147], v[240:243], v[120:123]
	v_mfma_f32_16x16x32_bf16 v[124:127], v[152:155], v[240:243], v[124:127]
	v_mfma_f32_16x16x32_bf16 v[32:35], v[156:159], v[212:215], v[32:35]
	v_mfma_f32_16x16x32_bf16 v[36:39], v[188:191], v[212:215], v[36:39]
	v_mfma_f32_16x16x32_bf16 v[52:55], v[156:159], v[220:223], v[52:55]
	v_mfma_f32_16x16x32_bf16 v[56:59], v[188:191], v[220:223], v[56:59]
	v_mfma_f32_16x16x32_bf16 v[72:75], v[156:159], v[228:231], v[72:75]
	v_mfma_f32_16x16x32_bf16 v[80:83], v[188:191], v[228:231], v[80:83]
	v_mfma_f32_16x16x32_bf16 v[88:91], v[156:159], v[236:239], v[88:91]
	v_mfma_f32_16x16x32_bf16 v[92:95], v[188:191], v[236:239], v[92:95]
	v_mfma_f32_16x16x32_bf16 v[32:35], v[184:187], v[216:219], v[32:35]
	v_mfma_f32_16x16x32_bf16 v[36:39], v[192:195], v[216:219], v[36:39]
	v_mfma_f32_16x16x32_bf16 v[52:55], v[184:187], v[224:227], v[52:55]
	v_mfma_f32_16x16x32_bf16 v[56:59], v[192:195], v[224:227], v[56:59]
	v_mfma_f32_16x16x32_bf16 v[72:75], v[184:187], v[232:235], v[72:75]
	v_mfma_f32_16x16x32_bf16 v[80:83], v[192:195], v[232:235], v[80:83]
	v_mfma_f32_16x16x32_bf16 v[88:91], v[184:187], v[240:243], v[88:91]
	v_mfma_f32_16x16x32_bf16 v[92:95], v[192:195], v[240:243], v[92:95]
	s_setprio 0
	s_barrier
	s_add_i32 s62, s62, s41
	v_lshl_add_u64 v[130:131], s[60:61], 0, v[178:179]
	s_mov_b32 m0, s62
	ds_read_b128 v[212:215], v143 offset:16384
	ds_read_b128 v[216:219], v143 offset:17408
	ds_read_b128 v[220:223], v143 offset:18432
	ds_read_b128 v[224:227], v143 offset:19456
	ds_read_b128 v[228:231], v143 offset:20480
	ds_read_b128 v[232:235], v143 offset:21504
	ds_read_b128 v[236:239], v143 offset:22528
	ds_read_b128 v[240:243], v143 offset:23552
	global_load_lds_dwordx4 v[130:131], off
	s_add_i32 m0, s62, 0x2000
	v_lshl_add_u64 v[160:161], s[60:61], 0, v[182:183]
	s_add_u32 s60, s60, s88
	s_addc_u32 s61, s61, 0
	s_add_i32 s62, s63, s41
	global_load_lds_dwordx4 v[160:161], off
	v_lshl_add_u64 v[244:245], s[60:61], 0, v[178:179]
	s_mov_b32 m0, s62
	v_lshl_add_u64 v[246:247], s[60:61], 0, v[182:183]
	global_load_lds_dwordx4 v[244:245], off
	s_add_i32 m0, s62, 0x2000
	v_lshl_add_u64 v[248:249], s[8:9], 0, v[176:177]
	global_load_lds_dwordx4 v[246:247], off
	s_mov_b32 m0, s44
	v_lshl_add_u64 v[250:251], s[8:9], 0, v[180:181]
	global_load_lds_dwordx4 v[248:249], off
	s_mov_b32 m0, s45
	s_nop 0
	global_load_lds_dwordx4 v[250:251], off
	s_waitcnt vmcnt(8)
	s_waitcnt lgkmcnt(0)
	s_barrier
; #define PG8_STAGE(bufoff, gbase, voff) do { _Pragma("unroll") for (int _i = 0; _i < 2; ++_i) \
;         __builtin_amdgcn_global_load_lds((const unsigned*)((const char*)(gbase) + (voff)[_i]), (PG8_LAS unsigned*)(lds + (bufoff) + ldsw + _i * 8192), 16, 0, 0); } while (0)
; #define PG8_LDA(dst, b, h) do { _Pragma("unroll") for (int m = 0; m < 4; ++m) _Pragma("unroll") for (int k = 0; k < 2; ++k) dst[m][k] = *(const PG8_LAS bf16x8*)(lds + PG8_SA(b, h) + aoff + m * 2048 + k * 1024); } while (0)
; #define PG8_LDB(dst, b, h) do { _Pragma("unroll") for (int n = 0; n < 2; ++n) _Pragma("unroll") for (int k = 0; k < 2; ++k) dst[n][k] = *(const PG8_LAS bf16x8*)(lds + PG8_SB(b, h) + boff + n * 2048 + k * 1024); } while (0)
; #define PG8_MMA(ai, bj, At, Bt) do { __builtin_amdgcn_s_setprio(1); _Pragma("unroll") for (int m = 0; m < 4; ++m) _Pragma("unroll") for (int n = 0; n < 2; ++n) _Pragma("unroll") for (int k = 0; k < 2; ++k) \
;         acc[ai][bj][m][n] = __builtin_amdgcn_mfma_f32_16x16x32_bf16(Bt[n][k], At[m][k], acc[ai][bj][m][n], 0, 0, 0); __builtin_amdgcn_s_setprio(0); } while (0)
; #define PG8_WAIT_V(n) asm volatile("s_waitcnt vmcnt(" #n ")" ::: "memory")
; #define PG8_WAIT_L(n) asm volatile("s_waitcnt lgkmcnt(" #n ")" ::: "memory")
; #define PG8_BAR __builtin_amdgcn_s_barrier()
; #define PG8_SCHED __builtin_amdgcn_sched_barrier(0)
; template <class Epi, class Sched, bool ALIGN_EPI = false, bool SP2 = false>
; __device__ __forceinline__ void gemm_phase(PG8_LAS unsigned char* lds, const Gemm g, const Sched& S, const Epi& E, const int wave_s) {
;     ...
;             PG8_WAIT_V(8); PG8_WAIT_L(0); PG8_BAR; PG8_MMA(1, 0, At, B0); PG8_MMA(1, 1, At, B1); PG8_BAR; PG8_SCHED;
;             PG8_LDB(B0, 1, 0); PG8_LDB(B1, 1, 1); PG8_SCHED; PG8_LDA(At, 1, 0); PG8_STAGE(PG8_SA(0, 1), a2 + hstep, voffA);
;             PG8_WAIT_V(8); PG8_WAIT_L(0); PG8_BAR; PG8_MMA(0, 0, At, B0); PG8_MMA(0, 1, At, B1); PG8_BAR; PG8_SCHED;
	s_setprio 1
	v_mfma_f32_16x16x32_bf16 v[84:87], v[138:141], v[212:215], v[84:87]
	v_mfma_f32_16x16x32_bf16 v[76:79], v[148:151], v[212:215], v[76:79]
	v_mfma_f32_16x16x32_bf16 v[68:71], v[138:141], v[220:223], v[68:71]
	v_mfma_f32_16x16x32_bf16 v[64:67], v[148:151], v[220:223], v[64:67]
	v_mfma_f32_16x16x32_bf16 v[60:63], v[138:141], v[228:231], v[60:63]
	v_mfma_f32_16x16x32_bf16 v[48:51], v[148:151], v[228:231], v[48:51]
	v_mfma_f32_16x16x32_bf16 v[44:47], v[138:141], v[236:239], v[44:47]
	v_mfma_f32_16x16x32_bf16 v[40:43], v[148:151], v[236:239], v[40:43]
	v_mfma_f32_16x16x32_bf16 v[84:87], v[144:147], v[216:219], v[84:87]
	v_mfma_f32_16x16x32_bf16 v[76:79], v[152:155], v[216:219], v[76:79]
	v_mfma_f32_16x16x32_bf16 v[68:71], v[144:147], v[224:227], v[68:71]
	v_mfma_f32_16x16x32_bf16 v[64:67], v[152:155], v[224:227], v[64:67]
	v_mfma_f32_16x16x32_bf16 v[60:63], v[144:147], v[232:235], v[60:63]
	v_mfma_f32_16x16x32_bf16 v[48:51], v[152:155], v[232:235], v[48:51]
	v_mfma_f32_16x16x32_bf16 v[44:47], v[144:147], v[240:243], v[44:47]
	v_mfma_f32_16x16x32_bf16 v[40:43], v[152:155], v[240:243], v[40:43]
	v_mfma_f32_16x16x32_bf16 v[28:31], v[156:159], v[212:215], v[28:31]
	v_mfma_f32_16x16x32_bf16 v[24:27], v[188:191], v[212:215], v[24:27]
	v_mfma_f32_16x16x32_bf16 v[20:23], v[156:159], v[220:223], v[20:23]
	v_mfma_f32_16x16x32_bf16 v[16:19], v[188:191], v[220:223], v[16:19]
	v_mfma_f32_16x16x32_bf16 v[12:15], v[156:159], v[228:231], v[12:15]
	v_mfma_f32_16x16x32_bf16 v[8:11], v[188:191], v[228:231], v[8:11]
	v_mfma_f32_16x16x32_bf16 v[4:7], v[156:159], v[236:239], v[4:7]
	v_mfma_f32_16x16x32_bf16 v[0:3], v[188:191], v[236:239], v[0:3]
	v_mfma_f32_16x16x32_bf16 v[28:31], v[184:187], v[216:219], v[28:31]
	v_mfma_f32_16x16x32_bf16 v[24:27], v[192:195], v[216:219], v[24:27]
	v_mfma_f32_16x16x32_bf16 v[20:23], v[184:187], v[224:227], v[20:23]
	v_mfma_f32_16x16x32_bf16 v[16:19], v[192:195], v[224:227], v[16:19]
	v_mfma_f32_16x16x32_bf16 v[12:15], v[184:187], v[232:235], v[12:15]
	v_mfma_f32_16x16x32_bf16 v[8:11], v[192:195], v[232:235], v[8:11]
	v_mfma_f32_16x16x32_bf16 v[4:7], v[184:187], v[240:243], v[4:7]
	v_mfma_f32_16x16x32_bf16 v[0:3], v[192:195], v[240:243], v[0:3]
	s_setprio 0
	s_barrier
	s_add_i32 s60, 0, 0x18000
	v_add_u32_e32 v128, s60, v142
	s_add_i32 s61, 0, 0x1c000
	ds_read_b128 v[138:141], v128
	ds_read_b128 v[144:147], v128 offset:1024
	ds_read_b128 v[148:151], v128 offset:2048
	ds_read_b128 v[152:155], v128 offset:3072
	v_add_u32_e32 v128, s61, v142
	ds_read_b128 v[156:159], v128
	ds_read_b128 v[184:187], v128 offset:1024
	ds_read_b128 v[188:191], v128 offset:2048
	ds_read_b128 v[192:195], v128 offset:3072
	s_add_u32 s8, s8, s88
	s_addc_u32 s9, s9, 0
	s_mov_b32 m0, s46
	v_lshl_add_u64 v[206:207], s[8:9], 0, v[176:177]
	ds_read_b128 v[212:215], v143 offset:32768
	ds_read_b128 v[216:219], v143 offset:33792
	ds_read_b128 v[220:223], v143 offset:34816
	ds_read_b128 v[224:227], v143 offset:35840
	ds_read_b128 v[228:231], v143 offset:36864
	ds_read_b128 v[232:235], v143 offset:37888
	ds_read_b128 v[236:239], v143 offset:38912
	ds_read_b128 v[240:243], v143 offset:39936
	global_load_lds_dwordx4 v[206:207], off
	v_lshl_add_u64 v[206:207], s[8:9], 0, v[180:181]
	s_mov_b32 m0, s47
	s_nop 0
	global_load_lds_dwordx4 v[206:207], off
	s_waitcnt vmcnt(8)
	s_waitcnt lgkmcnt(0)
	s_barrier
	s_setprio 1
	v_mfma_f32_16x16x32_bf16 v[96:99], v[138:141], v[212:215], v[96:99]
	v_mfma_f32_16x16x32_bf16 v[100:103], v[148:151], v[212:215], v[100:103]
	v_mfma_f32_16x16x32_bf16 v[104:107], v[138:141], v[220:223], v[104:107]
	v_mfma_f32_16x16x32_bf16 v[108:111], v[148:151], v[220:223], v[108:111]
	v_mfma_f32_16x16x32_bf16 v[112:115], v[138:141], v[228:231], v[112:115]
	v_mfma_f32_16x16x32_bf16 v[116:119], v[148:151], v[228:231], v[116:119]
	v_mfma_f32_16x16x32_bf16 v[120:123], v[138:141], v[236:239], v[120:123]
	v_mfma_f32_16x16x32_bf16 v[124:127], v[148:151], v[236:239], v[124:127]
	v_mfma_f32_16x16x32_bf16 v[96:99], v[144:147], v[216:219], v[96:99]
	v_mfma_f32_16x16x32_bf16 v[100:103], v[152:155], v[216:219], v[100:103]
	v_mfma_f32_16x16x32_bf16 v[104:107], v[144:147], v[224:227], v[104:107]
	v_mfma_f32_16x16x32_bf16 v[108:111], v[152:155], v[224:227], v[108:111]
	v_mfma_f32_16x16x32_bf16 v[112:115], v[144:147], v[232:235], v[112:115]
	v_mfma_f32_16x16x32_bf16 v[116:119], v[152:155], v[232:235], v[116:119]
	v_mfma_f32_16x16x32_bf16 v[120:123], v[144:147], v[240:243], v[120:123]
	v_mfma_f32_16x16x32_bf16 v[124:127], v[152:155], v[240:243], v[124:127]
	v_mfma_f32_16x16x32_bf16 v[32:35], v[156:159], v[212:215], v[32:35]
	v_mfma_f32_16x16x32_bf16 v[36:39], v[188:191], v[212:215], v[36:39]
	v_mfma_f32_16x16x32_bf16 v[52:55], v[156:159], v[220:223], v[52:55]
	v_mfma_f32_16x16x32_bf16 v[56:59], v[188:191], v[220:223], v[56:59]
	v_mfma_f32_16x16x32_bf16 v[72:75], v[156:159], v[228:231], v[72:75]
	v_mfma_f32_16x16x32_bf16 v[80:83], v[188:191], v[228:231], v[80:83]
	v_mfma_f32_16x16x32_bf16 v[88:91], v[156:159], v[236:239], v[88:91]
	v_mfma_f32_16x16x32_bf16 v[92:95], v[188:191], v[236:239], v[92:95]
	v_mfma_f32_16x16x32_bf16 v[32:35], v[184:187], v[216:219], v[32:35]
	v_mfma_f32_16x16x32_bf16 v[36:39], v[192:195], v[216:219], v[36:39]
	v_mfma_f32_16x16x32_bf16 v[52:55], v[184:187], v[224:227], v[52:55]
	v_mfma_f32_16x16x32_bf16 v[56:59], v[192:195], v[224:227], v[56:59]
	v_mfma_f32_16x16x32_bf16 v[72:75], v[184:187], v[232:235], v[72:75]
	v_mfma_f32_16x16x32_bf16 v[80:83], v[192:195], v[232:235], v[80:83]
	v_mfma_f32_16x16x32_bf16 v[88:91], v[184:187], v[240:243], v[88:91]
	v_mfma_f32_16x16x32_bf16 v[92:95], v[192:195], v[240:243], v[92:95]
	s_setprio 0
	s_barrier
; #define PG8_STAGE(bufoff, gbase, voff) do { _Pragma("unroll") for (int _i = 0; _i < 2; ++_i) \
;         __builtin_amdgcn_global_load_lds((const unsigned*)((const char*)(gbase) + (voff)[_i]), (PG8_LAS unsigned*)(lds + (bufoff) + ldsw + _i * 8192), 16, 0, 0); } while (0)
; #define PG8_LDA(dst, b, h) do { _Pragma("unroll") for (int m = 0; m < 4; ++m) _Pragma("unroll") for (int k = 0; k < 2; ++k) dst[m][k] = *(const PG8_LAS bf16x8*)(lds + PG8_SA(b, h) + aoff + m * 2048 + k * 1024); } while (0)
; #define PG8_MMA(ai, bj, At, Bt) do { __builtin_amdgcn_s_setprio(1); _Pragma("unroll") for (int m = 0; m < 4; ++m) _Pragma("unroll") for (int n = 0; n < 2; ++n) _Pragma("unroll") for (int k = 0; k < 2; ++k) \
;         acc[ai][bj][m][n] = __builtin_amdgcn_mfma_f32_16x16x32_bf16(Bt[n][k], At[m][k], acc[ai][bj][m][n], 0, 0, 0); __builtin_amdgcn_s_setprio(0); } while (0)
; #define PG8_WAIT_V(n) asm volatile("s_waitcnt vmcnt(" #n ")" ::: "memory")
; #define PG8_WAIT_L(n) asm volatile("s_waitcnt lgkmcnt(" #n ")" ::: "memory")
; #define PG8_BAR __builtin_amdgcn_s_barrier()
; #define PG8_SCHED __builtin_amdgcn_sched_barrier(0)
; template <class Epi, class Sched, bool ALIGN_EPI = false, bool SP2 = false>
; __device__ __forceinline__ void gemm_phase(PG8_LAS unsigned char* lds, const Gemm g, const Sched& S, const Epi& E, const int wave_s) {
;     ...
;             PG8_LDA(At, 1, 1); PG8_STAGE(PG8_SB(1, 0), b3, voffB); PG8_STAGE(PG8_SB(1, 1), b3 + hstep, voffB); PG8_STAGE(PG8_SA(1, 0), a3, voffA);
;             PG8_WAIT_V(8); PG8_WAIT_L(0); PG8_BAR; PG8_MMA(1, 0, At, B0); PG8_MMA(1, 1, At, B1); PG8_BAR; PG8_SCHED;
	s_add_i32 s8, s60, s41
	v_lshl_add_u64 v[130:131], v[130:131], 0, s[4:5]
	s_mov_b32 m0, s8
	ds_read_b128 v[212:215], v143 offset:49152
	ds_read_b128 v[216:219], v143 offset:50176
	ds_read_b128 v[220:223], v143 offset:51200
	ds_read_b128 v[224:227], v143 offset:52224
	ds_read_b128 v[228:231], v143 offset:53248
	ds_read_b128 v[232:235], v143 offset:54272
	ds_read_b128 v[236:239], v143 offset:55296
	ds_read_b128 v[240:243], v143 offset:56320
	global_load_lds_dwordx4 v[130:131], off
	v_lshl_add_u64 v[130:131], v[160:161], 0, s[4:5]
	s_add_i32 m0, s8, 0x2000
	s_add_i32 s8, s61, s41
	global_load_lds_dwordx4 v[130:131], off
	v_lshl_add_u64 v[130:131], v[244:245], 0, s[4:5]
	s_mov_b32 m0, s8
	s_nop 0
	global_load_lds_dwordx4 v[130:131], off
	v_lshl_add_u64 v[130:131], v[246:247], 0, s[4:5]
	s_add_i32 m0, s8, 0x2000
	s_nop 0
	global_load_lds_dwordx4 v[130:131], off
	v_lshl_add_u64 v[130:131], v[248:249], 0, s[4:5]
	s_mov_b32 m0, s48
	s_nop 0
	global_load_lds_dwordx4 v[130:131], off
	v_lshl_add_u64 v[130:131], v[250:251], 0, s[4:5]
	s_mov_b32 m0, s49
	s_nop 0
	global_load_lds_dwordx4 v[130:131], off
	s_waitcnt vmcnt(8)
	s_waitcnt lgkmcnt(0)
	s_barrier
	s_setprio 1
	v_mfma_f32_16x16x32_bf16 v[84:87], v[138:141], v[212:215], v[84:87]
	v_mfma_f32_16x16x32_bf16 v[76:79], v[148:151], v[212:215], v[76:79]
	v_mfma_f32_16x16x32_bf16 v[68:71], v[138:141], v[220:223], v[68:71]
	v_mfma_f32_16x16x32_bf16 v[64:67], v[148:151], v[220:223], v[64:67]
	v_mfma_f32_16x16x32_bf16 v[60:63], v[138:141], v[228:231], v[60:63]
	v_mfma_f32_16x16x32_bf16 v[48:51], v[148:151], v[228:231], v[48:51]
	v_mfma_f32_16x16x32_bf16 v[44:47], v[138:141], v[236:239], v[44:47]
	v_mfma_f32_16x16x32_bf16 v[40:43], v[148:151], v[236:239], v[40:43]
	v_mfma_f32_16x16x32_bf16 v[84:87], v[144:147], v[216:219], v[84:87]
	v_mfma_f32_16x16x32_bf16 v[76:79], v[152:155], v[216:219], v[76:79]
	v_mfma_f32_16x16x32_bf16 v[68:71], v[144:147], v[224:227], v[68:71]
	v_mfma_f32_16x16x32_bf16 v[64:67], v[152:155], v[224:227], v[64:67]
	v_mfma_f32_16x16x32_bf16 v[60:63], v[144:147], v[232:235], v[60:63]
	v_mfma_f32_16x16x32_bf16 v[48:51], v[152:155], v[232:235], v[48:51]
	v_mfma_f32_16x16x32_bf16 v[44:47], v[144:147], v[240:243], v[44:47]
	v_mfma_f32_16x16x32_bf16 v[40:43], v[152:155], v[240:243], v[40:43]
	v_mfma_f32_16x16x32_bf16 v[28:31], v[156:159], v[212:215], v[28:31]
	v_mfma_f32_16x16x32_bf16 v[24:27], v[188:191], v[212:215], v[24:27]
	v_mfma_f32_16x16x32_bf16 v[20:23], v[156:159], v[220:223], v[20:23]
	v_mfma_f32_16x16x32_bf16 v[16:19], v[188:191], v[220:223], v[16:19]
	v_mfma_f32_16x16x32_bf16 v[12:15], v[156:159], v[228:231], v[12:15]
	v_mfma_f32_16x16x32_bf16 v[8:11], v[188:191], v[228:231], v[8:11]
	v_mfma_f32_16x16x32_bf16 v[4:7], v[156:159], v[236:239], v[4:7]
	v_mfma_f32_16x16x32_bf16 v[0:3], v[188:191], v[236:239], v[0:3]
	v_mfma_f32_16x16x32_bf16 v[28:31], v[184:187], v[216:219], v[28:31]
	v_mfma_f32_16x16x32_bf16 v[24:27], v[192:195], v[216:219], v[24:27]
	v_mfma_f32_16x16x32_bf16 v[20:23], v[184:187], v[224:227], v[20:23]
	v_mfma_f32_16x16x32_bf16 v[16:19], v[192:195], v[224:227], v[16:19]
	v_mfma_f32_16x16x32_bf16 v[12:15], v[184:187], v[232:235], v[12:15]
	v_mfma_f32_16x16x32_bf16 v[8:11], v[192:195], v[232:235], v[8:11]
	v_mfma_f32_16x16x32_bf16 v[4:7], v[184:187], v[240:243], v[4:7]
	v_mfma_f32_16x16x32_bf16 v[0:3], v[192:195], v[240:243], v[0:3]
	s_setprio 0
	s_barrier
	s_add_u32 s34, s34, 0x100
	s_addc_u32 s35, s35, 0
	s_add_u32 s57, s57, 0x100
	s_addc_u32 s58, s58, 0
	s_cmp_ge_i32 s59, s55
	s_mov_b32 s8, s59
	s_cbranch_scc0 .LBB0_369
	s_and_b64 vcc, exec, s[26:27]
	s_cbranch_vccz .LBB0_372
	s_barrier

; #define PG8_STAGE(bufoff, gbase, voff) do { _Pragma("unroll") for (int _i = 0; _i < 2; ++_i) \
;         __builtin_amdgcn_global_load_lds((const unsigned*)((const char*)(gbase) + (voff)[_i]), (PG8_LAS unsigned*)(lds + (bufoff) + ldsw + _i * 8192), 16, 0, 0); } while (0)
; #define PG8_LDA(dst, b, h) do { _Pragma("unroll") for (int m = 0; m < 4; ++m) _Pragma("unroll") for (int k = 0; k < 2; ++k) dst[m][k] = *(const PG8_LAS bf16x8*)(lds + PG8_SA(b, h) + aoff + m * 2048 + k * 1024); } while (0)
; #define PG8_LDB(dst, b, h) do { _Pragma("unroll") for (int n = 0; n < 2; ++n) _Pragma("unroll") for (int k = 0; k < 2; ++k) dst[n][k] = *(const PG8_LAS bf16x8*)(lds + PG8_SB(b, h) + boff + n * 2048 + k * 1024); } while (0)
; #define PG8_MMA(ai, bj, At, Bt) do { __builtin_amdgcn_s_setprio(1); _Pragma("unroll") for (int m = 0; m < 4; ++m) _Pragma("unroll") for (int n = 0; n < 2; ++n) _Pragma("unroll") for (int k = 0; k < 2; ++k) \
;         acc[ai][bj][m][n] = __builtin_amdgcn_mfma_f32_16x16x32_bf16(Bt[n][k], At[m][k], acc[ai][bj][m][n], 0, 0, 0); __builtin_amdgcn_s_setprio(0); } while (0)
; #define PG8_WAIT_V(n) asm volatile("s_waitcnt vmcnt(" #n ")" ::: "memory")
; #define PG8_WAIT_L(n) asm volatile("s_waitcnt lgkmcnt(" #n ")" ::: "memory")
; #define PG8_BAR __builtin_amdgcn_s_barrier()
; template <class Epi, class Sched, bool ALIGN_EPI = false, bool SP2 = false>
; __device__ __forceinline__ void gemm_phase(PG8_LAS unsigned char* lds, const Gemm g, const Sched& S, const Epi& E, const int wave_s) {
;     ...
;             const char* a1 = cA + (size_t)(t + 1) * kstep;
;             const char* a2 = last ? nA : cA + (size_t)(t + 2) * kstep; const char* b2 = last ? nB : cB + (size_t)(t + 2) * kstep;
;             const char* a3 = a2 + kstep; const char* b3 = b2 + kstep;
;             if (last && has_next) S.a_ready(nxt);
;             if constexpr (SP2) {
;             PG8_LDB(B0, 0, 0); PG8_LDB(B1, 0, 1); PG8_SCHED; PG8_LDA(At, 0, 0); PG8_STAGE(PG8_SA(1, 1), a1 + hstep, voffA);
;             PG8_WAIT_V(8); PG8_WAIT_L(0); PG8_BAR; PG8_MMA(0, 0, At, B0); PG8_MMA(0, 1, At, B1); PG8_BAR; PG8_SCHED;
;             PG8_LDA(At, 0, 1); PG8_STAGE(PG8_SB(0, 0), b2, voffB); PG8_STAGE(PG8_SB(0, 1), b2 + hstep, voffB); PG8_STAGE(PG8_SA(0, 0), a2, voffA);
;             PG8_WAIT_V(8); PG8_WAIT_L(0); PG8_BAR; PG8_MMA(1, 0, At, B0); PG8_MMA(1, 1, At, B1); PG8_BAR; PG8_SCHED;
.LBB0_523:
	s_add_u32 s2, s24, 0xfffc0080
	s_addc_u32 s3, s25, -1
	s_add_i32 s51, 0, 0x10000
	s_cmp_eq_u32 s50, 12
	s_cselect_b32 s27, s19, s3
	s_cselect_b32 s26, s46, s2
	v_add_u32_e32 v144, s51, v147
	s_cselect_b32 s3, s17, s49
	s_cselect_b32 s2, s47, s48
	s_add_i32 s54, 0, 0x14000
	ds_read_b128 v[140:143], v144
	ds_read_b128 v[150:153], v144 offset:1024
	ds_read_b128 v[154:157], v144 offset:2048
	ds_read_b128 v[158:161], v144 offset:3072
	v_add_u32_e32 v144, s54, v147
	ds_read_b128 v[174:177], v144
	ds_read_b128 v[178:181], v144 offset:1024
	ds_read_b128 v[182:185], v144 offset:2048
	ds_read_b128 v[186:189], v144 offset:3072
	v_lshl_add_u64 v[194:195], s[24:25], 0, v[136:137]
	s_add_i32 m0, s35, 0xc000
	ds_read_b128 v[190:193], v148
	ds_read_b128 v[210:213], v148 offset:1024
	ds_read_b128 v[214:217], v148 offset:2048
	ds_read_b128 v[218:221], v148 offset:3072
	ds_read_b128 v[222:225], v148 offset:4096
	ds_read_b128 v[226:229], v148 offset:5120
	ds_read_b128 v[230:233], v148 offset:6144
	ds_read_b128 v[234:237], v148 offset:7168
	global_load_lds_dwordx4 v[194:195], off
	v_lshl_add_u64 v[194:195], s[24:25], 0, v[138:139]
	s_add_i32 m0, s35, 0xe000
	s_nop 0
	global_load_lds_dwordx4 v[194:195], off
	s_waitcnt vmcnt(8)
	s_waitcnt lgkmcnt(0)
	s_barrier
	s_setprio 1
	v_mfma_f32_16x16x32_bf16 v[124:127], v[140:143], v[190:193], v[124:127]
	v_mfma_f32_16x16x32_bf16 v[116:119], v[154:157], v[190:193], v[116:119]
	v_mfma_f32_16x16x32_bf16 v[108:111], v[140:143], v[214:217], v[108:111]
	v_mfma_f32_16x16x32_bf16 v[100:103], v[154:157], v[214:217], v[100:103]
	v_mfma_f32_16x16x32_bf16 v[92:95], v[140:143], v[222:225], v[92:95]
	v_mfma_f32_16x16x32_bf16 v[84:87], v[154:157], v[222:225], v[84:87]
	v_mfma_f32_16x16x32_bf16 v[76:79], v[140:143], v[230:233], v[76:79]
	v_mfma_f32_16x16x32_bf16 v[68:71], v[154:157], v[230:233], v[68:71]
	v_mfma_f32_16x16x32_bf16 v[124:127], v[150:153], v[210:213], v[124:127]
	v_mfma_f32_16x16x32_bf16 v[116:119], v[158:161], v[210:213], v[116:119]
	v_mfma_f32_16x16x32_bf16 v[108:111], v[150:153], v[218:221], v[108:111]
	v_mfma_f32_16x16x32_bf16 v[100:103], v[158:161], v[218:221], v[100:103]
	v_mfma_f32_16x16x32_bf16 v[92:95], v[150:153], v[226:229], v[92:95]
	v_mfma_f32_16x16x32_bf16 v[84:87], v[158:161], v[226:229], v[84:87]
	v_mfma_f32_16x16x32_bf16 v[76:79], v[150:153], v[234:237], v[76:79]
	v_mfma_f32_16x16x32_bf16 v[68:71], v[158:161], v[234:237], v[68:71]
	v_mfma_f32_16x16x32_bf16 v[120:123], v[174:177], v[190:193], v[120:123]
	v_mfma_f32_16x16x32_bf16 v[112:115], v[182:185], v[190:193], v[112:115]
	v_mfma_f32_16x16x32_bf16 v[104:107], v[174:177], v[214:217], v[104:107]
	v_mfma_f32_16x16x32_bf16 v[96:99], v[182:185], v[214:217], v[96:99]
	v_mfma_f32_16x16x32_bf16 v[88:91], v[174:177], v[222:225], v[88:91]
	v_mfma_f32_16x16x32_bf16 v[80:83], v[182:185], v[222:225], v[80:83]
	v_mfma_f32_16x16x32_bf16 v[72:75], v[174:177], v[230:233], v[72:75]
	v_mfma_f32_16x16x32_bf16 v[64:67], v[182:185], v[230:233], v[64:67]
	v_mfma_f32_16x16x32_bf16 v[120:123], v[178:181], v[210:213], v[120:123]
	v_mfma_f32_16x16x32_bf16 v[112:115], v[186:189], v[210:213], v[112:115]
	v_mfma_f32_16x16x32_bf16 v[104:107], v[178:181], v[218:221], v[104:107]
	v_mfma_f32_16x16x32_bf16 v[96:99], v[186:189], v[218:221], v[96:99]
	v_mfma_f32_16x16x32_bf16 v[88:91], v[178:181], v[226:229], v[88:91]
	v_mfma_f32_16x16x32_bf16 v[80:83], v[186:189], v[226:229], v[80:83]
	v_mfma_f32_16x16x32_bf16 v[72:75], v[178:181], v[234:237], v[72:75]
	v_mfma_f32_16x16x32_bf16 v[64:67], v[186:189], v[234:237], v[64:67]
	s_setprio 0
	s_barrier
	s_add_i32 s51, s51, s34
	v_lshl_add_u64 v[194:195], s[2:3], 0, v[128:129]
	s_mov_b32 m0, s51
	ds_read_b128 v[190:193], v148 offset:16384
	ds_read_b128 v[210:213], v148 offset:17408
	ds_read_b128 v[214:217], v148 offset:18432
	ds_read_b128 v[218:221], v148 offset:19456
	ds_read_b128 v[222:225], v148 offset:20480
	ds_read_b128 v[226:229], v148 offset:21504
	ds_read_b128 v[230:233], v148 offset:22528
	ds_read_b128 v[234:237], v148 offset:23552
	global_load_lds_dwordx4 v[194:195], off
	s_add_i32 m0, s51, 0x2000
	s_add_u32 s52, s2, 0x40000
	v_lshl_add_u64 v[238:239], s[2:3], 0, v[130:131]
	s_addc_u32 s53, s3, 0
	s_add_i32 s51, s54, s34
	global_load_lds_dwordx4 v[238:239], off
	v_lshl_add_u64 v[240:241], s[52:53], 0, v[128:129]
	s_mov_b32 m0, s51
	v_lshl_add_u64 v[242:243], s[26:27], 0, v[132:133]
	global_load_lds_dwordx4 v[240:241], off
	v_lshl_add_u64 v[240:241], s[52:53], 0, v[130:131]
	s_add_i32 m0, s51, 0x2000
	s_nop 0
	global_load_lds_dwordx4 v[240:241], off
	v_lshl_add_u64 v[240:241], s[26:27], 0, v[134:135]
	s_mov_b32 m0, s35
	s_nop 0
	global_load_lds_dwordx4 v[240:241], off
	s_mov_b32 m0, s36
	s_nop 0
	global_load_lds_dwordx4 v[242:243], off
	s_waitcnt vmcnt(8)
	s_waitcnt lgkmcnt(0)
	s_barrier
; #define PG8_STAGE(bufoff, gbase, voff) do { _Pragma("unroll") for (int _i = 0; _i < 2; ++_i) \
;         __builtin_amdgcn_global_load_lds((const unsigned*)((const char*)(gbase) + (voff)[_i]), (PG8_LAS unsigned*)(lds + (bufoff) + ldsw + _i * 8192), 16, 0, 0); } while (0)
; #define PG8_LDA(dst, b, h) do { _Pragma("unroll") for (int m = 0; m < 4; ++m) _Pragma("unroll") for (int k = 0; k < 2; ++k) dst[m][k] = *(const PG8_LAS bf16x8*)(lds + PG8_SA(b, h) + aoff + m * 2048 + k * 1024); } while (0)
; #define PG8_LDB(dst, b, h) do { _Pragma("unroll") for (int n = 0; n < 2; ++n) _Pragma("unroll") for (int k = 0; k < 2; ++k) dst[n][k] = *(const PG8_LAS bf16x8*)(lds + PG8_SB(b, h) + boff + n * 2048 + k * 1024); } while (0)
; #define PG8_MMA(ai, bj, At, Bt) do { __builtin_amdgcn_s_setprio(1); _Pragma("unroll") for (int m = 0; m < 4; ++m) _Pragma("unroll") for (int n = 0; n < 2; ++n) _Pragma("unroll") for (int k = 0; k < 2; ++k) \
;         acc[ai][bj][m][n] = __builtin_amdgcn_mfma_f32_16x16x32_bf16(Bt[n][k], At[m][k], acc[ai][bj][m][n], 0, 0, 0); __builtin_amdgcn_s_setprio(0); } while (0)
; #define PG8_WAIT_V(n) asm volatile("s_waitcnt vmcnt(" #n ")" ::: "memory")
; #define PG8_WAIT_L(n) asm volatile("s_waitcnt lgkmcnt(" #n ")" ::: "memory")
; #define PG8_BAR __builtin_amdgcn_s_barrier()
; #define PG8_SCHED __builtin_amdgcn_sched_barrier(0)
; template <class Epi, class Sched, bool ALIGN_EPI = false, bool SP2 = false>
; __device__ __forceinline__ void gemm_phase(PG8_LAS unsigned char* lds, const Gemm g, const Sched& S, const Epi& E, const int wave_s) {
;     ...
;             PG8_WAIT_V(8); PG8_WAIT_L(0); PG8_BAR; PG8_MMA(1, 0, At, B0); PG8_MMA(1, 1, At, B1); PG8_BAR; PG8_SCHED;
;             PG8_LDB(B0, 1, 0); PG8_LDB(B1, 1, 1); PG8_SCHED; PG8_LDA(At, 1, 0); PG8_STAGE(PG8_SA(0, 1), a2 + hstep, voffA);
;             PG8_WAIT_V(8); PG8_WAIT_L(0); PG8_BAR; PG8_MMA(0, 0, At, B0); PG8_MMA(0, 1, At, B1); PG8_BAR; PG8_SCHED;
	s_setprio 1
	v_mfma_f32_16x16x32_bf16 v[60:63], v[140:143], v[190:193], v[60:63]
	v_mfma_f32_16x16x32_bf16 v[52:55], v[154:157], v[190:193], v[52:55]
	v_mfma_f32_16x16x32_bf16 v[44:47], v[140:143], v[214:217], v[44:47]
	v_mfma_f32_16x16x32_bf16 v[36:39], v[154:157], v[214:217], v[36:39]
	v_mfma_f32_16x16x32_bf16 v[28:31], v[140:143], v[222:225], v[28:31]
	v_mfma_f32_16x16x32_bf16 v[20:23], v[154:157], v[222:225], v[20:23]
	v_mfma_f32_16x16x32_bf16 v[12:15], v[140:143], v[230:233], v[12:15]
	v_mfma_f32_16x16x32_bf16 v[4:7], v[154:157], v[230:233], v[4:7]
	v_mfma_f32_16x16x32_bf16 v[60:63], v[150:153], v[210:213], v[60:63]
	v_mfma_f32_16x16x32_bf16 v[52:55], v[158:161], v[210:213], v[52:55]
	v_mfma_f32_16x16x32_bf16 v[44:47], v[150:153], v[218:221], v[44:47]
	v_mfma_f32_16x16x32_bf16 v[36:39], v[158:161], v[218:221], v[36:39]
	v_mfma_f32_16x16x32_bf16 v[28:31], v[150:153], v[226:229], v[28:31]
	v_mfma_f32_16x16x32_bf16 v[20:23], v[158:161], v[226:229], v[20:23]
	v_mfma_f32_16x16x32_bf16 v[12:15], v[150:153], v[234:237], v[12:15]
	v_mfma_f32_16x16x32_bf16 v[4:7], v[158:161], v[234:237], v[4:7]
	v_mfma_f32_16x16x32_bf16 v[56:59], v[174:177], v[190:193], v[56:59]
	v_mfma_f32_16x16x32_bf16 v[48:51], v[182:185], v[190:193], v[48:51]
	v_mfma_f32_16x16x32_bf16 v[40:43], v[174:177], v[214:217], v[40:43]
	v_mfma_f32_16x16x32_bf16 v[32:35], v[182:185], v[214:217], v[32:35]
	v_mfma_f32_16x16x32_bf16 v[24:27], v[174:177], v[222:225], v[24:27]
	v_mfma_f32_16x16x32_bf16 v[16:19], v[182:185], v[222:225], v[16:19]
	v_mfma_f32_16x16x32_bf16 v[8:11], v[174:177], v[230:233], v[8:11]
	v_mfma_f32_16x16x32_bf16 v[0:3], v[182:185], v[230:233], v[0:3]
	v_mfma_f32_16x16x32_bf16 v[56:59], v[178:181], v[210:213], v[56:59]
	v_mfma_f32_16x16x32_bf16 v[48:51], v[186:189], v[210:213], v[48:51]
	v_mfma_f32_16x16x32_bf16 v[40:43], v[178:181], v[218:221], v[40:43]
	v_mfma_f32_16x16x32_bf16 v[32:35], v[186:189], v[218:221], v[32:35]
	v_mfma_f32_16x16x32_bf16 v[24:27], v[178:181], v[226:229], v[24:27]
	v_mfma_f32_16x16x32_bf16 v[16:19], v[186:189], v[226:229], v[16:19]
	v_mfma_f32_16x16x32_bf16 v[8:11], v[178:181], v[234:237], v[8:11]
	v_mfma_f32_16x16x32_bf16 v[0:3], v[186:189], v[234:237], v[0:3]
	s_setprio 0
	s_barrier
	s_add_i32 s51, 0, 0x18000
	v_add_u32_e32 v144, s51, v147
	s_add_i32 s52, 0, 0x1c000
	ds_read_b128 v[140:143], v144
	ds_read_b128 v[150:153], v144 offset:1024
	ds_read_b128 v[154:157], v144 offset:2048
	ds_read_b128 v[158:161], v144 offset:3072
	v_add_u32_e32 v144, s52, v147
	ds_read_b128 v[174:177], v144
	ds_read_b128 v[178:181], v144 offset:1024
	ds_read_b128 v[182:185], v144 offset:2048
	ds_read_b128 v[186:189], v144 offset:3072
	s_add_u32 s26, s26, 0x40000
	s_addc_u32 s27, s27, 0
	s_mov_b32 m0, s37
	v_lshl_add_u64 v[244:245], s[26:27], 0, v[134:135]
	ds_read_b128 v[190:193], v148 offset:32768
	ds_read_b128 v[210:213], v148 offset:33792
	ds_read_b128 v[214:217], v148 offset:34816
	ds_read_b128 v[218:221], v148 offset:35840
	ds_read_b128 v[222:225], v148 offset:36864
	ds_read_b128 v[226:229], v148 offset:37888
	ds_read_b128 v[230:233], v148 offset:38912
	ds_read_b128 v[234:237], v148 offset:39936
	global_load_lds_dwordx4 v[244:245], off
	v_lshl_add_u64 v[244:245], s[26:27], 0, v[132:133]
	s_mov_b32 m0, s38
	s_nop 0
	global_load_lds_dwordx4 v[244:245], off
	s_waitcnt vmcnt(8)
	s_waitcnt lgkmcnt(0)
	s_barrier
	s_setprio 1
	v_mfma_f32_16x16x32_bf16 v[124:127], v[140:143], v[190:193], v[124:127]
	v_mfma_f32_16x16x32_bf16 v[116:119], v[154:157], v[190:193], v[116:119]
	v_mfma_f32_16x16x32_bf16 v[108:111], v[140:143], v[214:217], v[108:111]
	v_mfma_f32_16x16x32_bf16 v[100:103], v[154:157], v[214:217], v[100:103]
	v_mfma_f32_16x16x32_bf16 v[92:95], v[140:143], v[222:225], v[92:95]
	v_mfma_f32_16x16x32_bf16 v[84:87], v[154:157], v[222:225], v[84:87]
	v_mfma_f32_16x16x32_bf16 v[76:79], v[140:143], v[230:233], v[76:79]
	v_mfma_f32_16x16x32_bf16 v[68:71], v[154:157], v[230:233], v[68:71]
	v_mfma_f32_16x16x32_bf16 v[124:127], v[150:153], v[210:213], v[124:127]
	v_mfma_f32_16x16x32_bf16 v[116:119], v[158:161], v[210:213], v[116:119]
	v_mfma_f32_16x16x32_bf16 v[108:111], v[150:153], v[218:221], v[108:111]
	v_mfma_f32_16x16x32_bf16 v[100:103], v[158:161], v[218:221], v[100:103]
	v_mfma_f32_16x16x32_bf16 v[92:95], v[150:153], v[226:229], v[92:95]
	v_mfma_f32_16x16x32_bf16 v[84:87], v[158:161], v[226:229], v[84:87]
	v_mfma_f32_16x16x32_bf16 v[76:79], v[150:153], v[234:237], v[76:79]
	v_mfma_f32_16x16x32_bf16 v[68:71], v[158:161], v[234:237], v[68:71]
	v_mfma_f32_16x16x32_bf16 v[120:123], v[174:177], v[190:193], v[120:123]
	v_mfma_f32_16x16x32_bf16 v[112:115], v[182:185], v[190:193], v[112:115]
	v_mfma_f32_16x16x32_bf16 v[104:107], v[174:177], v[214:217], v[104:107]
	v_mfma_f32_16x16x32_bf16 v[96:99], v[182:185], v[214:217], v[96:99]
	v_mfma_f32_16x16x32_bf16 v[88:91], v[174:177], v[222:225], v[88:91]
	v_mfma_f32_16x16x32_bf16 v[80:83], v[182:185], v[222:225], v[80:83]
	v_mfma_f32_16x16x32_bf16 v[72:75], v[174:177], v[230:233], v[72:75]
	v_mfma_f32_16x16x32_bf16 v[64:67], v[182:185], v[230:233], v[64:67]
	v_mfma_f32_16x16x32_bf16 v[120:123], v[178:181], v[210:213], v[120:123]
	v_mfma_f32_16x16x32_bf16 v[112:115], v[186:189], v[210:213], v[112:115]
	v_mfma_f32_16x16x32_bf16 v[104:107], v[178:181], v[218:221], v[104:107]
	v_mfma_f32_16x16x32_bf16 v[96:99], v[186:189], v[218:221], v[96:99]
	v_mfma_f32_16x16x32_bf16 v[88:91], v[178:181], v[226:229], v[88:91]
	v_mfma_f32_16x16x32_bf16 v[80:83], v[186:189], v[226:229], v[80:83]
	v_mfma_f32_16x16x32_bf16 v[72:75], v[178:181], v[234:237], v[72:75]
	v_mfma_f32_16x16x32_bf16 v[64:67], v[186:189], v[234:237], v[64:67]
	s_setprio 0
	s_barrier
; #define PG8_STAGE(bufoff, gbase, voff) do { _Pragma("unroll") for (int _i = 0; _i < 2; ++_i) \
;         __builtin_amdgcn_global_load_lds((const unsigned*)((const char*)(gbase) + (voff)[_i]), (PG8_LAS unsigned*)(lds + (bufoff) + ldsw + _i * 8192), 16, 0, 0); } while (0)
; #define PG8_LDA(dst, b, h) do { _Pragma("unroll") for (int m = 0; m < 4; ++m) _Pragma("unroll") for (int k = 0; k < 2; ++k) dst[m][k] = *(const PG8_LAS bf16x8*)(lds + PG8_SA(b, h) + aoff + m * 2048 + k * 1024); } while (0)
; #define PG8_MMA(ai, bj, At, Bt) do { __builtin_amdgcn_s_setprio(1); _Pragma("unroll") for (int m = 0; m < 4; ++m) _Pragma("unroll") for (int n = 0; n < 2; ++n) _Pragma("unroll") for (int k = 0; k < 2; ++k) \
;         acc[ai][bj][m][n] = __builtin_amdgcn_mfma_f32_16x16x32_bf16(Bt[n][k], At[m][k], acc[ai][bj][m][n], 0, 0, 0); __builtin_amdgcn_s_setprio(0); } while (0)
; #define PG8_WAIT_V(n) asm volatile("s_waitcnt vmcnt(" #n ")" ::: "memory")
; #define PG8_WAIT_L(n) asm volatile("s_waitcnt lgkmcnt(" #n ")" ::: "memory")
; #define PG8_BAR __builtin_amdgcn_s_barrier()
; #define PG8_SCHED __builtin_amdgcn_sched_barrier(0)
; template <class Epi, class Sched, bool ALIGN_EPI = false, bool SP2 = false>
; __device__ __forceinline__ void gemm_phase(PG8_LAS unsigned char* lds, const Gemm g, const Sched& S, const Epi& E, const int wave_s) {
;     ...
;             PG8_LDA(At, 1, 1); PG8_STAGE(PG8_SB(1, 0), b3, voffB); PG8_STAGE(PG8_SB(1, 1), b3 + hstep, voffB); PG8_STAGE(PG8_SA(1, 0), a3, voffA);
;             PG8_WAIT_V(8); PG8_WAIT_L(0); PG8_BAR; PG8_MMA(1, 0, At, B0); PG8_MMA(1, 1, At, B1); PG8_BAR; PG8_SCHED;
	s_add_i32 s26, s51, s34
	v_lshl_add_u64 v[194:195], v[194:195], 0, s[4:5]
	s_mov_b32 m0, s26
	ds_read_b128 v[190:193], v148 offset:49152
	ds_read_b128 v[210:213], v148 offset:50176
	ds_read_b128 v[214:217], v148 offset:51200
	ds_read_b128 v[218:221], v148 offset:52224
	ds_read_b128 v[222:225], v148 offset:53248
	ds_read_b128 v[226:229], v148 offset:54272
	ds_read_b128 v[230:233], v148 offset:55296
	ds_read_b128 v[234:237], v148 offset:56320
	global_load_lds_dwordx4 v[194:195], off
	s_add_i32 m0, s26, 0x2000
	s_add_u32 s2, s2, 0x40080
	v_lshl_add_u64 v[194:195], v[238:239], 0, s[4:5]
	s_addc_u32 s3, s3, 0
	s_add_i32 s26, s52, s34
	global_load_lds_dwordx4 v[194:195], off
	v_lshl_add_u64 v[194:195], s[2:3], 0, v[128:129]
	s_mov_b32 m0, s26
	s_nop 0
	global_load_lds_dwordx4 v[194:195], off
	v_lshl_add_u64 v[194:195], s[2:3], 0, v[130:131]
	s_add_i32 m0, s26, 0x2000
	s_nop 0
	global_load_lds_dwordx4 v[194:195], off
	v_lshl_add_u64 v[194:195], v[240:241], 0, s[4:5]
	s_mov_b32 m0, s41
	s_nop 0
	global_load_lds_dwordx4 v[194:195], off
	v_lshl_add_u64 v[194:195], v[242:243], 0, s[4:5]
	s_mov_b32 m0, s42
	s_nop 0
	global_load_lds_dwordx4 v[194:195], off
	s_waitcnt vmcnt(8)
	s_waitcnt lgkmcnt(0)
	s_barrier
	s_setprio 1
	v_mfma_f32_16x16x32_bf16 v[60:63], v[140:143], v[190:193], v[60:63]
	v_mfma_f32_16x16x32_bf16 v[52:55], v[154:157], v[190:193], v[52:55]
	v_mfma_f32_16x16x32_bf16 v[44:47], v[140:143], v[214:217], v[44:47]
	v_mfma_f32_16x16x32_bf16 v[36:39], v[154:157], v[214:217], v[36:39]
	v_mfma_f32_16x16x32_bf16 v[28:31], v[140:143], v[222:225], v[28:31]
	v_mfma_f32_16x16x32_bf16 v[20:23], v[154:157], v[222:225], v[20:23]
	v_mfma_f32_16x16x32_bf16 v[12:15], v[140:143], v[230:233], v[12:15]
	v_mfma_f32_16x16x32_bf16 v[4:7], v[154:157], v[230:233], v[4:7]
	v_mfma_f32_16x16x32_bf16 v[60:63], v[150:153], v[210:213], v[60:63]
	v_mfma_f32_16x16x32_bf16 v[52:55], v[158:161], v[210:213], v[52:55]
	v_mfma_f32_16x16x32_bf16 v[44:47], v[150:153], v[218:221], v[44:47]
	v_mfma_f32_16x16x32_bf16 v[36:39], v[158:161], v[218:221], v[36:39]
	v_mfma_f32_16x16x32_bf16 v[28:31], v[150:153], v[226:229], v[28:31]
	v_mfma_f32_16x16x32_bf16 v[20:23], v[158:161], v[226:229], v[20:23]
	v_mfma_f32_16x16x32_bf16 v[12:15], v[150:153], v[234:237], v[12:15]
	v_mfma_f32_16x16x32_bf16 v[4:7], v[158:161], v[234:237], v[4:7]
	v_mfma_f32_16x16x32_bf16 v[56:59], v[174:177], v[190:193], v[56:59]
	v_mfma_f32_16x16x32_bf16 v[48:51], v[182:185], v[190:193], v[48:51]
	v_mfma_f32_16x16x32_bf16 v[40:43], v[174:177], v[214:217], v[40:43]
	v_mfma_f32_16x16x32_bf16 v[32:35], v[182:185], v[214:217], v[32:35]
	v_mfma_f32_16x16x32_bf16 v[24:27], v[174:177], v[222:225], v[24:27]
	v_mfma_f32_16x16x32_bf16 v[16:19], v[182:185], v[222:225], v[16:19]
	v_mfma_f32_16x16x32_bf16 v[8:11], v[174:177], v[230:233], v[8:11]
	v_mfma_f32_16x16x32_bf16 v[0:3], v[182:185], v[230:233], v[0:3]
	v_mfma_f32_16x16x32_bf16 v[56:59], v[178:181], v[210:213], v[56:59]
	v_mfma_f32_16x16x32_bf16 v[48:51], v[186:189], v[210:213], v[48:51]
	v_mfma_f32_16x16x32_bf16 v[40:43], v[178:181], v[218:221], v[40:43]
	v_mfma_f32_16x16x32_bf16 v[32:35], v[186:189], v[218:221], v[32:35]
	v_mfma_f32_16x16x32_bf16 v[24:27], v[178:181], v[226:229], v[24:27]
	v_mfma_f32_16x16x32_bf16 v[16:19], v[186:189], v[226:229], v[16:19]
	v_mfma_f32_16x16x32_bf16 v[8:11], v[178:181], v[234:237], v[8:11]
	v_mfma_f32_16x16x32_bf16 v[0:3], v[186:189], v[234:237], v[0:3]
	s_setprio 0
	s_barrier
	s_add_i32 s50, s50, 2
	s_add_u32 s24, s24, 0x100
	s_addc_u32 s25, s25, 0
	s_add_u32 s48, s48, 0x100
	s_addc_u32 s49, s49, 0
	s_cmp_gt_u32 s50, 13
	s_cbranch_scc0 .LBB0_523
	s_and_b64 vcc, exec, s[14:15]
	s_cbranch_vccz .LBB0_526
	s_barrier
